# D/WOUT prologues: the vmcnt(0) before the residual start values becomes vmcnt(6) (it also waited for K-tile 1's LDS-DMA pieces issued just before it)
# speedup vs baseline: 1.0104x; 1.0104x over previous
; #define PG8_STAGE(bufoff, gbase, voff) do { _Pragma("unroll") for (int _i = 0; _i < 2; ++_i) \
;         __builtin_amdgcn_global_load_lds((const unsigned*)((const char*)(gbase) + (voff)[_i]), (PG8_LAS unsigned*)(lds + (bufoff) + ldsw + _i * 8192), 16, 0, 0); } while (0)
; #define PG8_WAIT_V(n) asm volatile("s_waitcnt vmcnt(" #n ")" ::: "memory")
; #define PG8_BAR __builtin_amdgcn_s_barrier()
; template <class Epi, class Sched, bool ALIGN_EPI = false, bool SP2 = false>
; __device__ __forceinline__ void gemm_phase(PG8_LAS unsigned char* lds, const Gemm g, const Sched& S, const Epi& E) {
;     ...
;         PG8_STAGE(PG8_SB(1, 0), cB + kstep, voffB); PG8_STAGE(PG8_SA(1, 0), cA + kstep, voffA); PG8_STAGE(PG8_SB(1, 1), cB + hstep + kstep, voffB);
;         PG8_WAIT_V(6); PG8_BAR;
;     __device__ __forceinline__ void finish(f32x4 (&acc)[2][2][4][2], const Pre& p) const {
; #pragma unroll
;         for (int ai = 0; ai < 2; ++ai)
; #pragma unroll
;             for (int m = 0; m < 4; ++m)
; #pragma unroll
;                 for (int bj = 0; bj < 2; ++bj) { float f[8]; unpack8(p.v[ai][m][bj], f);
;                     acc[ai][bj][m][0] = (f32x4){f[0], f[1], f[2], f[3]} * inv_alpha; acc[ai][bj][m][1] = (f32x4){f[4], f[5], f[6], f[7]} * inv_alpha; }
;     }
.LBB0_1552:
	v_or_b32_e32 v142, s5, v64
	v_lshlrev_b32_e32 v65, 6, v142
	v_lshlrev_b32_e32 v74, 4, v134
	s_movk_i32 s5, 0x3c0
	v_lshlrev_b32_e32 v75, 2, v142
	v_readlane_b32 s6, v255, 14
	v_and_or_b32 v65, v65, s5, v74
	s_lshl_b32 s4, s4, 13
	v_and_b32_e32 v75, 32, v75
	v_readlane_b32 s7, v255, 15
	v_bitop3_b32 v151, v65, s4, v75 bitop3:0xde
	v_lshl_or_b32 v65, v64, 6, v74
	v_lshlrev_b32_e32 v64, 2, v64
	v_lshl_add_u64 v[66:67], s[6:7], 0, v[144:145]
	v_mov_b32_e32 v129, v145
	v_readlane_b32 s28, v253, 26
	s_lshl_b32 s4, s24, 12
	v_and_b32_e32 v64, 32, v64
	v_lshl_add_u64 v[68:69], s[6:7], 0, v[128:129]
	v_mov_b32_e32 v133, v145
	v_readlane_b32 s29, v253, 27
	v_bitop3_b32 v143, v65, s4, v64 bitop3:0xde
	s_add_i32 m0, s26, 0x18000
	v_lshl_add_u64 v[64:65], v[66:67], 0, s[94:95]
	v_lshl_add_u64 v[70:71], s[28:29], 0, v[132:133]
	v_mov_b32_e32 v131, v145
	s_waitcnt vmcnt(2)
	s_barrier
	global_load_lds_dwordx4 v[64:65], off
	v_lshl_add_u64 v[64:65], v[68:69], 0, s[94:95]
	s_add_i32 m0, s26, 0x1a000
	s_add_i32 s34, s26, 0x8000
	v_lshl_add_u64 v[72:73], s[28:29], 0, v[130:131]
	global_load_lds_dwordx4 v[64:65], off
	v_lshl_add_u64 v[64:65], v[70:71], 0, s[94:95]
	s_mov_b32 m0, s34
	s_add_i32 s35, s26, 0xa000
	v_readlane_b32 s4, v255, 16
	global_load_lds_dwordx4 v[64:65], off
	v_lshl_add_u64 v[64:65], v[72:73], 0, s[94:95]
	s_mov_b32 m0, s35
	v_readlane_b32 s5, v255, 17
	global_load_lds_dwordx4 v[64:65], off
	s_add_i32 m0, s26, 0x1c000
	v_lshl_add_u64 v[64:65], s[4:5], 0, v[144:145]
	global_load_lds_dwordx4 v[64:65], off
	v_lshl_add_u64 v[64:65], s[4:5], 0, v[128:129]
	s_add_i32 m0, s26, 0x1e000
	s_nop 0
	global_load_lds_dwordx4 v[64:65], off
	s_waitcnt vmcnt(6)
	s_barrier
	s_waitcnt vmcnt(6)
	v_lshlrev_b32_e32 v120, 16, v60
	v_and_b32_e32 v121, 0xffff0000, v60
	v_lshlrev_b32_e32 v122, 16, v61
	v_and_b32_e32 v123, 0xffff0000, v61
	v_lshlrev_b32_e32 v124, 16, v62
	v_and_b32_e32 v125, 0xffff0000, v62
	v_lshlrev_b32_e32 v126, 16, v63
	v_and_b32_e32 v127, 0xffff0000, v63
	v_lshlrev_b32_e32 v112, 16, v56
	v_and_b32_e32 v113, 0xffff0000, v56
	v_lshlrev_b32_e32 v114, 16, v57
	v_and_b32_e32 v115, 0xffff0000, v57
	v_lshlrev_b32_e32 v116, 16, v58
	v_and_b32_e32 v117, 0xffff0000, v58
	v_lshlrev_b32_e32 v118, 16, v59
	v_and_b32_e32 v119, 0xffff0000, v59
	v_lshlrev_b32_e32 v100, 16, v52
	v_and_b32_e32 v101, 0xffff0000, v52
	v_lshlrev_b32_e32 v102, 16, v53
	v_and_b32_e32 v103, 0xffff0000, v53
	v_lshlrev_b32_e32 v104, 16, v54
	v_and_b32_e32 v105, 0xffff0000, v54
	v_lshlrev_b32_e32 v106, 16, v55
	v_and_b32_e32 v107, 0xffff0000, v55
	v_lshlrev_b32_e32 v96, 16, v48
	v_and_b32_e32 v97, 0xffff0000, v48
	v_lshlrev_b32_e32 v98, 16, v49
	v_and_b32_e32 v99, 0xffff0000, v49
	v_lshlrev_b32_e32 v108, 16, v50
	v_and_b32_e32 v109, 0xffff0000, v50
	v_lshlrev_b32_e32 v110, 16, v51
	v_and_b32_e32 v111, 0xffff0000, v51
	v_lshlrev_b32_e32 v84, 16, v44
	v_and_b32_e32 v85, 0xffff0000, v44
	v_lshlrev_b32_e32 v86, 16, v45
	v_and_b32_e32 v87, 0xffff0000, v45
	v_lshlrev_b32_e32 v88, 16, v46
	v_and_b32_e32 v89, 0xffff0000, v46
	v_lshlrev_b32_e32 v90, 16, v47
	v_and_b32_e32 v91, 0xffff0000, v47
	v_lshlrev_b32_e32 v80, 16, v40
	v_and_b32_e32 v81, 0xffff0000, v40
	v_lshlrev_b32_e32 v82, 16, v41
	v_and_b32_e32 v83, 0xffff0000, v41
	v_lshlrev_b32_e32 v92, 16, v42
	v_and_b32_e32 v93, 0xffff0000, v42
	v_lshlrev_b32_e32 v94, 16, v43
	v_and_b32_e32 v95, 0xffff0000, v43
	v_lshlrev_b32_e32 v68, 16, v36
	v_and_b32_e32 v69, 0xffff0000, v36
	v_lshlrev_b32_e32 v70, 16, v37
	v_and_b32_e32 v71, 0xffff0000, v37
	v_lshlrev_b32_e32 v72, 16, v38
	v_and_b32_e32 v73, 0xffff0000, v38
	v_lshlrev_b32_e32 v74, 16, v39
	v_and_b32_e32 v75, 0xffff0000, v39
	v_lshlrev_b32_e32 v64, 16, v28
	v_and_b32_e32 v65, 0xffff0000, v28
	v_lshlrev_b32_e32 v66, 16, v29
	v_and_b32_e32 v67, 0xffff0000, v29
	v_lshlrev_b32_e32 v76, 16, v30
	v_and_b32_e32 v77, 0xffff0000, v30
	v_lshlrev_b32_e32 v78, 16, v31
	v_and_b32_e32 v79, 0xffff0000, v31
	v_lshlrev_b32_e32 v52, 16, v32
	v_and_b32_e32 v53, 0xffff0000, v32
	v_lshlrev_b32_e32 v54, 16, v33
	v_and_b32_e32 v55, 0xffff0000, v33
	v_lshlrev_b32_e32 v56, 16, v34
	v_and_b32_e32 v57, 0xffff0000, v34
	v_lshlrev_b32_e32 v58, 16, v35
	v_and_b32_e32 v59, 0xffff0000, v35
	v_lshlrev_b32_e32 v48, 16, v20
	v_and_b32_e32 v49, 0xffff0000, v20
	v_lshlrev_b32_e32 v50, 16, v21
	v_and_b32_e32 v51, 0xffff0000, v21
	v_lshlrev_b32_e32 v60, 16, v22
	v_and_b32_e32 v61, 0xffff0000, v22
	v_lshlrev_b32_e32 v62, 16, v23
	v_and_b32_e32 v63, 0xffff0000, v23
	v_lshlrev_b32_e32 v36, 16, v24
	v_and_b32_e32 v37, 0xffff0000, v24
	v_lshlrev_b32_e32 v38, 16, v25
	v_and_b32_e32 v39, 0xffff0000, v25
	v_lshlrev_b32_e32 v40, 16, v26
	v_and_b32_e32 v41, 0xffff0000, v26
	v_lshlrev_b32_e32 v42, 16, v27
	v_and_b32_e32 v43, 0xffff0000, v27
	v_lshlrev_b32_e32 v32, 16, v4
	v_and_b32_e32 v33, 0xffff0000, v4
	v_lshlrev_b32_e32 v34, 16, v5
	v_and_b32_e32 v35, 0xffff0000, v5
	v_lshlrev_b32_e32 v44, 16, v6
	v_and_b32_e32 v45, 0xffff0000, v6
	v_lshlrev_b32_e32 v46, 16, v7
	v_and_b32_e32 v47, 0xffff0000, v7
	v_lshlrev_b32_e32 v20, 16, v16
	v_and_b32_e32 v21, 0xffff0000, v16
	v_lshlrev_b32_e32 v22, 16, v17
	v_and_b32_e32 v23, 0xffff0000, v17
	v_lshlrev_b32_e32 v24, 16, v18
	v_and_b32_e32 v25, 0xffff0000, v18
	v_lshlrev_b32_e32 v26, 16, v19
	v_and_b32_e32 v27, 0xffff0000, v19
	v_lshlrev_b32_e32 v16, 16, v0
	v_and_b32_e32 v17, 0xffff0000, v0
	v_lshlrev_b32_e32 v18, 16, v1
	v_and_b32_e32 v19, 0xffff0000, v1
	v_lshlrev_b32_e32 v28, 16, v2
	v_and_b32_e32 v29, 0xffff0000, v2
	v_lshlrev_b32_e32 v30, 16, v3
	v_and_b32_e32 v31, 0xffff0000, v3
	v_lshlrev_b32_e32 v4, 16, v8
	v_and_b32_e32 v5, 0xffff0000, v8
	v_lshlrev_b32_e32 v6, 16, v9
	v_and_b32_e32 v7, 0xffff0000, v9
	v_lshlrev_b32_e32 v8, 16, v10
	v_and_b32_e32 v9, 0xffff0000, v10
	v_lshlrev_b32_e32 v10, 16, v11
	v_and_b32_e32 v11, 0xffff0000, v11
	v_lshlrev_b32_e32 v0, 16, v12
	v_and_b32_e32 v1, 0xffff0000, v12
	v_lshlrev_b32_e32 v2, 16, v13
	v_and_b32_e32 v3, 0xffff0000, v13
	v_lshlrev_b32_e32 v12, 16, v14
	v_and_b32_e32 v13, 0xffff0000, v14
	v_lshlrev_b32_e32 v14, 16, v15
	v_and_b32_e32 v15, 0xffff0000, v15
	v_cmp_eq_u32_e64 s[36:37], 0, v134
	v_lshlrev_b32_e32 v134, 14, v140
	v_and_b32_e32 v134, 0xffff8000, v134
	v_lshl_add_u32 v134, v139, 11, v134
	v_lshlrev_b32_e32 v139, 14, v136
	v_and_b32_e32 v139, 0xffff8000, v139
	v_or_b32_e32 v150, s1, v135
	v_and_b32_e32 v135, 1, v140
	v_lshl_add_u32 v137, v137, 11, v139
	v_and_b32_e32 v136, 1, v136
	s_cmpk_lt_u32 s0, 0x100
	v_lshl_or_b32 v134, v135, 6, v134
	v_lshl_or_b32 v136, v136, 6, v137
	v_readlane_b32 s0, v253, 30
	s_cselect_b64 s[42:43], -1, 0
	s_mov_b32 s50, 0
	v_lshl_add_u32 v134, v141, 1, v134
	v_mov_b32_e32 v135, v145
	v_lshl_add_u32 v136, v138, 1, v136
	v_mov_b32_e32 v137, v145
	v_add_u32_e32 v151, 0, v151
	s_mov_b32 s52, s0
	v_readlane_b32 s51, v253, 24
	v_readlane_b32 s1, v253, 31
	s_branch .LBB0_1555

; #define PG8_STAGE(bufoff, gbase, voff) do { _Pragma("unroll") for (int _i = 0; _i < 2; ++_i) \
;         __builtin_amdgcn_global_load_lds((const unsigned*)((const char*)(gbase) + (voff)[_i]), (PG8_LAS unsigned*)(lds + (bufoff) + ldsw + _i * 8192), 16, 0, 0); } while (0)
; #define PG8_WAIT_V(n) asm volatile("s_waitcnt vmcnt(" #n ")" ::: "memory")
; #define PG8_BAR __builtin_amdgcn_s_barrier()
; template <class Epi, class Sched, bool ALIGN_EPI = false, bool SP2 = false>
; __device__ __forceinline__ void gemm_phase(PG8_LAS unsigned char* lds, const Gemm g, const Sched& S, const Epi& E) {
;     ...
;         PG8_STAGE(PG8_SB(1, 0), cB + kstep, voffB); PG8_STAGE(PG8_SA(1, 0), cA + kstep, voffA); PG8_STAGE(PG8_SB(1, 1), cB + hstep + kstep, voffB);
;         PG8_WAIT_V(6); PG8_BAR;
;     __device__ __forceinline__ void finish(f32x4 (&acc)[2][2][4][2], const Pre& p) const {
; #pragma unroll
;         for (int ai = 0; ai < 2; ++ai)
; #pragma unroll
;             for (int m = 0; m < 4; ++m)
; #pragma unroll
;                 for (int bj = 0; bj < 2; ++bj) { float f[8]; unpack8(p.v[ai][m][bj], f);
;                     acc[ai][bj][m][0] = (f32x4){f[0], f[1], f[2], f[3]} * inv_alpha; acc[ai][bj][m][1] = (f32x4){f[4], f[5], f[6], f[7]} * inv_alpha; }
;     }
.LBB0_1886:
	v_or_b32_e32 v142, s7, v68
	v_lshlrev_b32_e32 v69, 6, v142
	v_lshlrev_b32_e32 v74, 4, v134
	s_movk_i32 s7, 0x3c0
	v_lshlrev_b32_e32 v75, 2, v142
	v_readlane_b32 s16, v253, 32
	v_and_or_b32 v69, v69, s7, v74
	s_lshl_b32 s6, s6, 13
	v_and_b32_e32 v75, 32, v75
	v_mov_b32_e32 v133, v145
	v_readlane_b32 s17, v253, 33
	v_bitop3_b32 v153, v69, s6, v75 bitop3:0xde
	v_lshl_or_b32 v69, v68, 6, v74
	v_lshlrev_b32_e32 v68, 2, v68
	s_add_i32 m0, s30, 0x18000
	v_lshl_add_u64 v[64:65], v[64:65], 0, s[94:95]
	v_lshl_add_u64 v[70:71], s[16:17], 0, v[132:133]
	v_mov_b32_e32 v131, v145
	s_lshl_b32 s6, s28, 12
	v_and_b32_e32 v68, 32, v68
	s_waitcnt vmcnt(2)
	s_barrier
	global_load_lds_dwordx4 v[64:65], off
	v_lshl_add_u64 v[64:65], v[66:67], 0, s[94:95]
	s_add_i32 m0, s30, 0x1a000
	s_add_i32 s50, s30, 0x8000
	s_add_i32 s51, s30, 0xa000
	v_lshl_add_u64 v[72:73], s[16:17], 0, v[130:131]
	v_bitop3_b32 v143, v69, s6, v68 bitop3:0xde
	global_load_lds_dwordx4 v[64:65], off
	v_lshl_add_u64 v[64:65], v[70:71], 0, s[94:95]
	s_mov_b32 m0, s50
	s_add_u32 s6, s4, 0xb0080
	global_load_lds_dwordx4 v[64:65], off
	v_lshl_add_u64 v[64:65], v[72:73], 0, s[94:95]
	s_mov_b32 m0, s51
	s_addc_u32 s7, s5, 0
	global_load_lds_dwordx4 v[64:65], off
	s_add_i32 m0, s30, 0x1c000
	v_lshl_add_u64 v[64:65], s[6:7], 0, v[144:145]
	global_load_lds_dwordx4 v[64:65], off
	v_lshl_add_u64 v[64:65], s[6:7], 0, v[128:129]
	s_add_i32 m0, s30, 0x1e000
	s_nop 0
	global_load_lds_dwordx4 v[64:65], off
	s_waitcnt vmcnt(6)
	s_barrier
	s_waitcnt vmcnt(6)
	v_lshlrev_b32_e32 v124, 16, v60
	v_and_b32_e32 v125, 0xffff0000, v60
	v_lshlrev_b32_e32 v126, 16, v61
	v_and_b32_e32 v127, 0xffff0000, v61
	v_lshlrev_b32_e32 v120, 16, v62
	v_and_b32_e32 v121, 0xffff0000, v62
	v_lshlrev_b32_e32 v122, 16, v63
	v_and_b32_e32 v123, 0xffff0000, v63
	v_lshlrev_b32_e32 v116, 16, v56
	v_and_b32_e32 v117, 0xffff0000, v56
	v_lshlrev_b32_e32 v118, 16, v57
	v_and_b32_e32 v119, 0xffff0000, v57
	v_lshlrev_b32_e32 v112, 16, v58
	v_and_b32_e32 v113, 0xffff0000, v58
	v_lshlrev_b32_e32 v114, 16, v59
	v_and_b32_e32 v115, 0xffff0000, v59
	v_lshlrev_b32_e32 v108, 16, v52
	v_and_b32_e32 v109, 0xffff0000, v52
	v_lshlrev_b32_e32 v110, 16, v53
	v_and_b32_e32 v111, 0xffff0000, v53
	v_lshlrev_b32_e32 v104, 16, v54
	v_and_b32_e32 v105, 0xffff0000, v54
	v_lshlrev_b32_e32 v106, 16, v55
	v_and_b32_e32 v107, 0xffff0000, v55
	v_lshlrev_b32_e32 v100, 16, v48
	v_and_b32_e32 v101, 0xffff0000, v48
	v_lshlrev_b32_e32 v102, 16, v49
	v_and_b32_e32 v103, 0xffff0000, v49
	v_lshlrev_b32_e32 v96, 16, v50
	v_and_b32_e32 v97, 0xffff0000, v50
	v_lshlrev_b32_e32 v98, 16, v51
	v_and_b32_e32 v99, 0xffff0000, v51
	v_lshlrev_b32_e32 v92, 16, v44
	v_and_b32_e32 v93, 0xffff0000, v44
	v_lshlrev_b32_e32 v94, 16, v45
	v_and_b32_e32 v95, 0xffff0000, v45
	v_lshlrev_b32_e32 v88, 16, v46
	v_and_b32_e32 v89, 0xffff0000, v46
	v_lshlrev_b32_e32 v90, 16, v47
	v_and_b32_e32 v91, 0xffff0000, v47
	v_lshlrev_b32_e32 v84, 16, v40
	v_and_b32_e32 v85, 0xffff0000, v40
	v_lshlrev_b32_e32 v86, 16, v41
	v_and_b32_e32 v87, 0xffff0000, v41
	v_lshlrev_b32_e32 v80, 16, v42
	v_and_b32_e32 v81, 0xffff0000, v42
	v_lshlrev_b32_e32 v82, 16, v43
	v_and_b32_e32 v83, 0xffff0000, v43
	v_lshlrev_b32_e32 v76, 16, v36
	v_and_b32_e32 v77, 0xffff0000, v36
	v_lshlrev_b32_e32 v78, 16, v37
	v_and_b32_e32 v79, 0xffff0000, v37
	v_lshlrev_b32_e32 v72, 16, v38
	v_and_b32_e32 v73, 0xffff0000, v38
	v_lshlrev_b32_e32 v74, 16, v39
	v_and_b32_e32 v75, 0xffff0000, v39
	v_lshlrev_b32_e32 v68, 16, v28
	v_and_b32_e32 v69, 0xffff0000, v28
	v_lshlrev_b32_e32 v70, 16, v29
	v_and_b32_e32 v71, 0xffff0000, v29
	v_lshlrev_b32_e32 v64, 16, v30
	v_and_b32_e32 v65, 0xffff0000, v30
	v_lshlrev_b32_e32 v66, 16, v31
	v_and_b32_e32 v67, 0xffff0000, v31
	v_lshlrev_b32_e32 v60, 16, v32
	v_and_b32_e32 v61, 0xffff0000, v32
	v_lshlrev_b32_e32 v62, 16, v33
	v_and_b32_e32 v63, 0xffff0000, v33
	v_lshlrev_b32_e32 v56, 16, v34
	v_and_b32_e32 v57, 0xffff0000, v34
	v_lshlrev_b32_e32 v58, 16, v35
	v_and_b32_e32 v59, 0xffff0000, v35
	v_lshlrev_b32_e32 v52, 16, v20
	v_and_b32_e32 v53, 0xffff0000, v20
	v_lshlrev_b32_e32 v54, 16, v21
	v_and_b32_e32 v55, 0xffff0000, v21
	v_lshlrev_b32_e32 v48, 16, v22
	v_and_b32_e32 v49, 0xffff0000, v22
	v_lshlrev_b32_e32 v50, 16, v23
	v_and_b32_e32 v51, 0xffff0000, v23
	v_lshlrev_b32_e32 v44, 16, v24
	v_and_b32_e32 v45, 0xffff0000, v24
	v_lshlrev_b32_e32 v46, 16, v25
	v_and_b32_e32 v47, 0xffff0000, v25
	v_lshlrev_b32_e32 v40, 16, v26
	v_and_b32_e32 v41, 0xffff0000, v26
	v_lshlrev_b32_e32 v42, 16, v27
	v_and_b32_e32 v43, 0xffff0000, v27
	v_lshlrev_b32_e32 v36, 16, v12
	v_and_b32_e32 v37, 0xffff0000, v12
	v_lshlrev_b32_e32 v38, 16, v13
	v_and_b32_e32 v39, 0xffff0000, v13
	v_lshlrev_b32_e32 v32, 16, v14
	v_and_b32_e32 v33, 0xffff0000, v14
	v_lshlrev_b32_e32 v34, 16, v15
	v_and_b32_e32 v35, 0xffff0000, v15
	v_lshlrev_b32_e32 v28, 16, v16
	v_and_b32_e32 v29, 0xffff0000, v16
	v_lshlrev_b32_e32 v30, 16, v17
	v_and_b32_e32 v31, 0xffff0000, v17
	v_lshlrev_b32_e32 v24, 16, v18
	v_and_b32_e32 v25, 0xffff0000, v18
	v_lshlrev_b32_e32 v26, 16, v19
	v_and_b32_e32 v27, 0xffff0000, v19
	v_lshlrev_b32_e32 v20, 16, v4
	v_and_b32_e32 v21, 0xffff0000, v4
	v_lshlrev_b32_e32 v22, 16, v5
	v_and_b32_e32 v23, 0xffff0000, v5
	v_lshlrev_b32_e32 v16, 16, v6
	v_and_b32_e32 v17, 0xffff0000, v6
	v_lshlrev_b32_e32 v18, 16, v7
	v_and_b32_e32 v19, 0xffff0000, v7
	v_lshlrev_b32_e32 v12, 16, v8
	v_and_b32_e32 v13, 0xffff0000, v8
	v_lshlrev_b32_e32 v14, 16, v9
	v_and_b32_e32 v15, 0xffff0000, v9
	v_lshlrev_b32_e32 v8, 16, v10
	v_and_b32_e32 v9, 0xffff0000, v10
	v_lshlrev_b32_e32 v10, 16, v11
	v_and_b32_e32 v11, 0xffff0000, v11
	v_lshlrev_b32_e32 v4, 16, v0
	v_and_b32_e32 v5, 0xffff0000, v0
	v_lshlrev_b32_e32 v6, 16, v1
	v_and_b32_e32 v7, 0xffff0000, v1
	v_lshlrev_b32_e32 v0, 16, v2
	v_and_b32_e32 v1, 0xffff0000, v2
	v_lshlrev_b32_e32 v2, 16, v3
	v_and_b32_e32 v3, 0xffff0000, v3
	s_movk_i32 s7, 0xb00
	v_cmp_eq_u32_e64 s[36:37], 0, v134
	v_or_b32_e32 v150, s1, v135
	v_lshrrev_b32_e32 v135, 1, v141
	v_mul_lo_u32 v134, v140, s7
	s_mov_b32 s6, 0xb000
	v_lshrrev_b32_e32 v140, 1, v136
	v_mul_lo_u32 v136, v137, s7
	s_cmpk_lt_u32 s0, 0x100
	v_mad_u64_u32 v[134:135], s[0:1], v135, s6, v[134:135]
	v_mad_u64_u32 v[136:137], s[0:1], v140, s6, v[136:137]
	v_or_b32_e32 v134, v134, v151
	v_or_b32_e32 v136, v136, v138
	v_add_lshl_u32 v134, v134, v152, 1
	v_mov_b32_e32 v135, v145
	s_mov_b64 s[18:19], 0xb0080
	v_add_lshl_u32 v136, v136, v139, 1
	v_mov_b32_e32 v137, v145
	v_readlane_b32 s0, v253, 30
	s_cselect_b64 s[46:47], -1, 0
	s_mov_b32 s52, 0
	v_lshl_add_u64 v[134:135], v[134:135], 0, s[18:19]
	v_lshl_add_u64 v[136:137], v[136:137], 0, s[18:19]
	v_add_u32_e32 v151, 0, v153
	s_mov_b32 s56, s0
	v_readlane_b32 s55, v253, 24
	s_mov_b64 s[6:7], s[16:17]
	v_readlane_b32 s1, v253, 31
	s_branch .LBB0_1889
